# GEMM k-loop: first half of the MFMAs issued under counted LDS waits before the mid-step barrier, DMA for k+2 interleaved with the second half
# baseline (speedup 1.0000x reference)
; template <class Epi>
; __device__ __forceinline__ void gemm_tile(const bf16_t* A, int lda, const bf16_t* Bt, int ldb, int K, int m0, int n0, const Epi& epi, char* smem) {
;     ...
;     for (int kt = 0; kt < nk; ++kt) {
;         const int st = (kt & 1) * 32768;
;         if (kt + 1 < nk) G_ISSUE(((kt + 1) & 1) * 32768, (kt + 1) * 64)
;         {
;             bf16x8 a0[4], b0[4], a1[4], b1[4];
;             const int ch0 = ((0 + fq) ^ rsw) << 4, ch1 = ((4 + fq) ^ rsw) << 4;
; #pragma unroll
;             for (int m = 0; m < 4; ++m) a0[m] = *(const bf16x8*)(smem + st + aofs + m * 2048 + ch0);
; #pragma unroll
;             for (int n = 0; n < 4; ++n) b0[n] = *(const bf16x8*)(smem + st + bofs + n * 2048 + ch0);
;             __builtin_amdgcn_sched_barrier(0);
; #pragma unroll
;             for (int m = 0; m < 4; ++m) a1[m] = *(const bf16x8*)(smem + st + aofs + m * 2048 + ch1);
; #pragma unroll
;             for (int n = 0; n < 4; ++n) b1[n] = *(const bf16x8*)(smem + st + bofs + n * 2048 + ch1);
;             __builtin_amdgcn_sched_barrier(0);
;             __builtin_amdgcn_s_setprio(1);
; #pragma unroll
;             for (int m = 0; m < 4; ++m)
; #pragma unroll
;                 for (int n = 0; n < 4; ++n) acc[m][n] = __builtin_amdgcn_mfma_f32_16x16x32_bf16(b0[n], a0[m], acc[m][n], 0, 0, 0);
;             __builtin_amdgcn_sched_barrier(0);
; #pragma unroll
;             for (int m = 0; m < 4; ++m)
; #pragma unroll
;                 for (int n = 0; n < 4; ++n) acc[m][n] = __builtin_amdgcn_mfma_f32_16x16x32_bf16(b1[n], a1[m], acc[m][n], 0, 0, 0);
;             __builtin_amdgcn_s_setprio(0);
;             __builtin_amdgcn_sched_barrier(0);
;         }
;         asm volatile("s_waitcnt vmcnt(0)" ::: "memory");
;         __syncthreads();
.LBB0_100:
	s_add_i32 s45, s44, 0xffff8000
	s_and_b32 s45, s45, 0x8000
	v_add_u32_e32 v89, s45, v88
	ds_read_b128 v[90:93], v89
	ds_read_b128 v[94:97], v89 offset:2048
	ds_read_b128 v[98:101], v89 offset:4096
	ds_read_b128 v[114:117], v89 offset:6144
	v_or_b32_e32 v89, s45, v87
	ds_read_b128 v[118:121], v89 offset:16384
	ds_read_b128 v[122:125], v89 offset:18432
	ds_read_b128 v[126:129], v89 offset:20480
	ds_read_b128 v[130:133], v89 offset:22528
	v_add_u32_e32 v89, s45, v86
	ds_read_b128 v[134:137], v89
	ds_read_b128 v[138:141], v89 offset:2048
	ds_read_b128 v[142:145], v89 offset:4096
	ds_read_b128 v[146:149], v89 offset:6144
	v_or_b32_e32 v89, s45, v85
	ds_read_b128 v[150:153], v89 offset:16384
	ds_read_b128 v[154:157], v89 offset:18432
	ds_read_b128 v[158:161], v89 offset:20480
	ds_read_b128 v[162:165], v89 offset:22528
	s_setprio 1
	s_waitcnt lgkmcnt(11)
	v_mfma_f32_16x16x32_bf16 v[36:39], v[118:121], v[90:93], v[36:39]
	s_waitcnt lgkmcnt(10)
	v_mfma_f32_16x16x32_bf16 v[24:27], v[122:125], v[90:93], v[24:27]
	s_waitcnt lgkmcnt(9)
	v_mfma_f32_16x16x32_bf16 v[20:23], v[126:129], v[90:93], v[20:23]
	s_waitcnt lgkmcnt(8)
	v_mfma_f32_16x16x32_bf16 v[16:19], v[130:133], v[90:93], v[16:19]
	v_mfma_f32_16x16x32_bf16 v[12:15], v[118:121], v[94:97], v[12:15]
	v_mfma_f32_16x16x32_bf16 v[8:11], v[122:125], v[94:97], v[8:11]
	v_mfma_f32_16x16x32_bf16 v[4:7], v[126:129], v[94:97], v[4:7]
	v_mfma_f32_16x16x32_bf16 v[0:3], v[130:133], v[94:97], v[0:3]
	v_mfma_f32_16x16x32_bf16 v[28:31], v[118:121], v[98:101], v[28:31]
	v_mfma_f32_16x16x32_bf16 v[32:35], v[122:125], v[98:101], v[32:35]
	v_mfma_f32_16x16x32_bf16 v[40:43], v[126:129], v[98:101], v[40:43]
	v_mfma_f32_16x16x32_bf16 v[44:47], v[130:133], v[98:101], v[44:47]
	v_mfma_f32_16x16x32_bf16 v[48:51], v[118:121], v[114:117], v[48:51]
	v_mfma_f32_16x16x32_bf16 v[52:55], v[122:125], v[114:117], v[52:55]
	v_mfma_f32_16x16x32_bf16 v[56:59], v[126:129], v[114:117], v[56:59]
	v_mfma_f32_16x16x32_bf16 v[60:63], v[130:133], v[114:117], v[60:63]
	s_setprio 0
	s_waitcnt lgkmcnt(0)
	s_barrier
	s_cmpk_eq_i32 s0, 0x1500
	s_cbranch_scc1 .Lnodma_g100
	s_add_u32 s100, s0, 0x80
	s_addc_u32 s101, s1, 0
	s_add_u32 s99, s98, s45
	s_setprio 1
	v_mfma_f32_16x16x32_bf16 v[36:39], v[150:153], v[134:137], v[36:39]
	v_mfma_f32_16x16x32_bf16 v[24:27], v[154:157], v[134:137], v[24:27]
	s_mov_b32 m0, s99
	v_lshl_add_u64 v[166:167], v[64:65], 0, s[100:101]
	global_load_lds_dwordx4 v[166:167], off
	v_mfma_f32_16x16x32_bf16 v[20:23], v[158:161], v[134:137], v[20:23]
	v_mfma_f32_16x16x32_bf16 v[16:19], v[162:165], v[134:137], v[16:19]
	s_add_u32 m0, s99, 0x4000
	v_lshl_add_u64 v[166:167], v[66:67], 0, s[100:101]
	global_load_lds_dwordx4 v[166:167], off
	v_mfma_f32_16x16x32_bf16 v[12:15], v[150:153], v[138:141], v[12:15]
	v_mfma_f32_16x16x32_bf16 v[8:11], v[154:157], v[138:141], v[8:11]
	s_add_u32 m0, s99, 0x1000
	v_lshl_add_u64 v[166:167], v[68:69], 0, s[100:101]
	global_load_lds_dwordx4 v[166:167], off
	v_mfma_f32_16x16x32_bf16 v[4:7], v[158:161], v[138:141], v[4:7]
	v_mfma_f32_16x16x32_bf16 v[0:3], v[162:165], v[138:141], v[0:3]
	s_add_u32 m0, s99, 0x5000
	v_lshl_add_u64 v[166:167], v[70:71], 0, s[100:101]
	global_load_lds_dwordx4 v[166:167], off
	v_mfma_f32_16x16x32_bf16 v[28:31], v[150:153], v[142:145], v[28:31]
	v_mfma_f32_16x16x32_bf16 v[32:35], v[154:157], v[142:145], v[32:35]
	s_add_u32 m0, s99, 0x2000
	v_lshl_add_u64 v[166:167], v[72:73], 0, s[100:101]
	global_load_lds_dwordx4 v[166:167], off
	v_mfma_f32_16x16x32_bf16 v[40:43], v[158:161], v[142:145], v[40:43]
	v_mfma_f32_16x16x32_bf16 v[44:47], v[162:165], v[142:145], v[44:47]
	s_add_u32 m0, s99, 0x6000
	v_lshl_add_u64 v[166:167], v[74:75], 0, s[100:101]
	global_load_lds_dwordx4 v[166:167], off
	v_mfma_f32_16x16x32_bf16 v[48:51], v[150:153], v[146:149], v[48:51]
	v_mfma_f32_16x16x32_bf16 v[52:55], v[154:157], v[146:149], v[52:55]
	s_add_u32 m0, s99, 0x3000
	v_lshl_add_u64 v[166:167], v[76:77], 0, s[100:101]
	global_load_lds_dwordx4 v[166:167], off
	v_mfma_f32_16x16x32_bf16 v[56:59], v[158:161], v[146:149], v[56:59]
	v_mfma_f32_16x16x32_bf16 v[60:63], v[162:165], v[146:149], v[60:63]
	s_add_u32 m0, s99, 0x7000
	v_lshl_add_u64 v[166:167], v[78:79], 0, s[100:101]
	global_load_lds_dwordx4 v[166:167], off
	s_setprio 0
	s_branch .Ljoin_g100
.Lnodma_g100:
	s_waitcnt vmcnt(0)
	s_setprio 1
	v_mfma_f32_16x16x32_bf16 v[36:39], v[150:153], v[134:137], v[36:39]
	v_mfma_f32_16x16x32_bf16 v[24:27], v[154:157], v[134:137], v[24:27]
	v_mfma_f32_16x16x32_bf16 v[20:23], v[158:161], v[134:137], v[20:23]
	v_mfma_f32_16x16x32_bf16 v[16:19], v[162:165], v[134:137], v[16:19]
	v_mfma_f32_16x16x32_bf16 v[12:15], v[150:153], v[138:141], v[12:15]
	v_mfma_f32_16x16x32_bf16 v[8:11], v[154:157], v[138:141], v[8:11]
	v_mfma_f32_16x16x32_bf16 v[4:7], v[158:161], v[138:141], v[4:7]
	v_mfma_f32_16x16x32_bf16 v[0:3], v[162:165], v[138:141], v[0:3]
	v_mfma_f32_16x16x32_bf16 v[28:31], v[150:153], v[142:145], v[28:31]
	v_mfma_f32_16x16x32_bf16 v[32:35], v[154:157], v[142:145], v[32:35]
	v_mfma_f32_16x16x32_bf16 v[40:43], v[158:161], v[142:145], v[40:43]
	v_mfma_f32_16x16x32_bf16 v[44:47], v[162:165], v[142:145], v[44:47]
	v_mfma_f32_16x16x32_bf16 v[48:51], v[150:153], v[146:149], v[48:51]
	v_mfma_f32_16x16x32_bf16 v[52:55], v[154:157], v[146:149], v[52:55]
	v_mfma_f32_16x16x32_bf16 v[56:59], v[158:161], v[146:149], v[56:59]
	v_mfma_f32_16x16x32_bf16 v[60:63], v[162:165], v[146:149], v[60:63]
	s_setprio 0

; template <class Epi>
; __device__ __forceinline__ void gemm_tile(const bf16_t* A, int lda, const bf16_t* Bt, int ldb, int K, int m0, int n0, const Epi& epi, char* smem) {
;     ...
;     for (int kt = 0; kt < nk; ++kt) {
;         const int st = (kt & 1) * 32768;
;         if (kt + 1 < nk) G_ISSUE(((kt + 1) & 1) * 32768, (kt + 1) * 64)
;         {
;             bf16x8 a0[4], b0[4], a1[4], b1[4];
;             const int ch0 = ((0 + fq) ^ rsw) << 4, ch1 = ((4 + fq) ^ rsw) << 4;
; #pragma unroll
;             for (int m = 0; m < 4; ++m) a0[m] = *(const bf16x8*)(smem + st + aofs + m * 2048 + ch0);
; #pragma unroll
;             for (int n = 0; n < 4; ++n) b0[n] = *(const bf16x8*)(smem + st + bofs + n * 2048 + ch0);
;             __builtin_amdgcn_sched_barrier(0);
; #pragma unroll
;             for (int m = 0; m < 4; ++m) a1[m] = *(const bf16x8*)(smem + st + aofs + m * 2048 + ch1);
; #pragma unroll
;             for (int n = 0; n < 4; ++n) b1[n] = *(const bf16x8*)(smem + st + bofs + n * 2048 + ch1);
;             __builtin_amdgcn_sched_barrier(0);
;             __builtin_amdgcn_s_setprio(1);
; #pragma unroll
;             for (int m = 0; m < 4; ++m)
; #pragma unroll
;                 for (int n = 0; n < 4; ++n) acc[m][n] = __builtin_amdgcn_mfma_f32_16x16x32_bf16(b0[n], a0[m], acc[m][n], 0, 0, 0);
;             __builtin_amdgcn_sched_barrier(0);
; #pragma unroll
;             for (int m = 0; m < 4; ++m)
; #pragma unroll
;                 for (int n = 0; n < 4; ++n) acc[m][n] = __builtin_amdgcn_mfma_f32_16x16x32_bf16(b1[n], a1[m], acc[m][n], 0, 0, 0);
;             __builtin_amdgcn_s_setprio(0);
;             __builtin_amdgcn_sched_barrier(0);
;         }
;         asm volatile("s_waitcnt vmcnt(0)" ::: "memory");
;         __syncthreads();
.LBB0_153:
	s_add_i32 s43, s42, 0xffff8000
	s_and_b32 s43, s43, 0x8000
	v_add_u32_e32 v89, s43, v87
	ds_read_b128 v[90:93], v89
	ds_read_b128 v[94:97], v89 offset:2048
	ds_read_b128 v[98:101], v89 offset:4096
	ds_read_b128 v[114:117], v89 offset:6144
	v_or_b32_e32 v89, s43, v88
	ds_read_b128 v[118:121], v89 offset:16384
	ds_read_b128 v[122:125], v89 offset:18432
	ds_read_b128 v[126:129], v89 offset:20480
	ds_read_b128 v[130:133], v89 offset:22528
	v_add_u32_e32 v89, s43, v86
	ds_read_b128 v[134:137], v89
	ds_read_b128 v[138:141], v89 offset:2048
	ds_read_b128 v[142:145], v89 offset:4096
	ds_read_b128 v[146:149], v89 offset:6144
	v_or_b32_e32 v89, s43, v85
	ds_read_b128 v[150:153], v89 offset:16384
	ds_read_b128 v[154:157], v89 offset:18432
	ds_read_b128 v[158:161], v89 offset:20480
	ds_read_b128 v[162:165], v89 offset:22528
	s_setprio 1
	s_waitcnt lgkmcnt(11)
	v_mfma_f32_16x16x32_bf16 v[36:39], v[118:121], v[90:93], v[36:39]
	s_waitcnt lgkmcnt(10)
	v_mfma_f32_16x16x32_bf16 v[24:27], v[122:125], v[90:93], v[24:27]
	s_waitcnt lgkmcnt(9)
	v_mfma_f32_16x16x32_bf16 v[20:23], v[126:129], v[90:93], v[20:23]
	s_waitcnt lgkmcnt(8)
	v_mfma_f32_16x16x32_bf16 v[16:19], v[130:133], v[90:93], v[16:19]
	v_mfma_f32_16x16x32_bf16 v[12:15], v[118:121], v[94:97], v[12:15]
	v_mfma_f32_16x16x32_bf16 v[8:11], v[122:125], v[94:97], v[8:11]
	v_mfma_f32_16x16x32_bf16 v[4:7], v[126:129], v[94:97], v[4:7]
	v_mfma_f32_16x16x32_bf16 v[0:3], v[130:133], v[94:97], v[0:3]
	v_mfma_f32_16x16x32_bf16 v[28:31], v[118:121], v[98:101], v[28:31]
	v_mfma_f32_16x16x32_bf16 v[32:35], v[122:125], v[98:101], v[32:35]
	v_mfma_f32_16x16x32_bf16 v[40:43], v[126:129], v[98:101], v[40:43]
	v_mfma_f32_16x16x32_bf16 v[44:47], v[130:133], v[98:101], v[44:47]
	v_mfma_f32_16x16x32_bf16 v[48:51], v[118:121], v[114:117], v[48:51]
	v_mfma_f32_16x16x32_bf16 v[52:55], v[122:125], v[114:117], v[52:55]
	v_mfma_f32_16x16x32_bf16 v[56:59], v[126:129], v[114:117], v[56:59]
	v_mfma_f32_16x16x32_bf16 v[60:63], v[130:133], v[114:117], v[60:63]
	s_setprio 0
	s_waitcnt lgkmcnt(0)
	s_barrier
	s_cmpk_eq_i32 s0, 0x700
	s_cbranch_scc1 .Lnodma_g153
	s_add_u32 s100, s0, 0x80
	s_addc_u32 s101, s1, 0
	s_add_u32 s99, s98, s43
	s_setprio 1
	v_mfma_f32_16x16x32_bf16 v[36:39], v[150:153], v[134:137], v[36:39]
	v_mfma_f32_16x16x32_bf16 v[24:27], v[154:157], v[134:137], v[24:27]
	s_mov_b32 m0, s99
	v_lshl_add_u64 v[166:167], v[64:65], 0, s[100:101]
	global_load_lds_dwordx4 v[166:167], off
	v_mfma_f32_16x16x32_bf16 v[20:23], v[158:161], v[134:137], v[20:23]
	v_mfma_f32_16x16x32_bf16 v[16:19], v[162:165], v[134:137], v[16:19]
	s_add_u32 m0, s99, 0x4000
	v_lshl_add_u64 v[166:167], v[66:67], 0, s[100:101]
	global_load_lds_dwordx4 v[166:167], off
	v_mfma_f32_16x16x32_bf16 v[12:15], v[150:153], v[138:141], v[12:15]
	v_mfma_f32_16x16x32_bf16 v[8:11], v[154:157], v[138:141], v[8:11]
	s_add_u32 m0, s99, 0x1000
	v_lshl_add_u64 v[166:167], v[68:69], 0, s[100:101]
	global_load_lds_dwordx4 v[166:167], off
	v_mfma_f32_16x16x32_bf16 v[4:7], v[158:161], v[138:141], v[4:7]
	v_mfma_f32_16x16x32_bf16 v[0:3], v[162:165], v[138:141], v[0:3]
	s_add_u32 m0, s99, 0x5000
	v_lshl_add_u64 v[166:167], v[70:71], 0, s[100:101]
	global_load_lds_dwordx4 v[166:167], off
	v_mfma_f32_16x16x32_bf16 v[28:31], v[150:153], v[142:145], v[28:31]
	v_mfma_f32_16x16x32_bf16 v[32:35], v[154:157], v[142:145], v[32:35]
	s_add_u32 m0, s99, 0x2000
	v_lshl_add_u64 v[166:167], v[72:73], 0, s[100:101]
	global_load_lds_dwordx4 v[166:167], off
	v_mfma_f32_16x16x32_bf16 v[40:43], v[158:161], v[142:145], v[40:43]
	v_mfma_f32_16x16x32_bf16 v[44:47], v[162:165], v[142:145], v[44:47]
	s_add_u32 m0, s99, 0x6000
	v_lshl_add_u64 v[166:167], v[74:75], 0, s[100:101]
	global_load_lds_dwordx4 v[166:167], off
	v_mfma_f32_16x16x32_bf16 v[48:51], v[150:153], v[146:149], v[48:51]
	v_mfma_f32_16x16x32_bf16 v[52:55], v[154:157], v[146:149], v[52:55]
	s_add_u32 m0, s99, 0x3000
	v_lshl_add_u64 v[166:167], v[76:77], 0, s[100:101]
	global_load_lds_dwordx4 v[166:167], off
	v_mfma_f32_16x16x32_bf16 v[56:59], v[158:161], v[146:149], v[56:59]
	v_mfma_f32_16x16x32_bf16 v[60:63], v[162:165], v[146:149], v[60:63]
	s_add_u32 m0, s99, 0x7000
	v_lshl_add_u64 v[166:167], v[78:79], 0, s[100:101]
	global_load_lds_dwordx4 v[166:167], off
	s_setprio 0
	s_branch .Ljoin_g153

; template <class Epi>
; __device__ __forceinline__ void gemm_tile(const bf16_t* A, int lda, const bf16_t* Bt, int ldb, int K, int m0, int n0, const Epi& epi, char* smem) {
;     ...
;     for (int kt = 0; kt < nk; ++kt) {
;         const int st = (kt & 1) * 32768;
;         if (kt + 1 < nk) G_ISSUE(((kt + 1) & 1) * 32768, (kt + 1) * 64)
;         {
;             bf16x8 a0[4], b0[4], a1[4], b1[4];
;             const int ch0 = ((0 + fq) ^ rsw) << 4, ch1 = ((4 + fq) ^ rsw) << 4;
; #pragma unroll
;             for (int m = 0; m < 4; ++m) a0[m] = *(const bf16x8*)(smem + st + aofs + m * 2048 + ch0);
; #pragma unroll
;             for (int n = 0; n < 4; ++n) b0[n] = *(const bf16x8*)(smem + st + bofs + n * 2048 + ch0);
;             __builtin_amdgcn_sched_barrier(0);
; #pragma unroll
;             for (int m = 0; m < 4; ++m) a1[m] = *(const bf16x8*)(smem + st + aofs + m * 2048 + ch1);
; #pragma unroll
;             for (int n = 0; n < 4; ++n) b1[n] = *(const bf16x8*)(smem + st + bofs + n * 2048 + ch1);
;             __builtin_amdgcn_sched_barrier(0);
;             __builtin_amdgcn_s_setprio(1);
; #pragma unroll
;             for (int m = 0; m < 4; ++m)
; #pragma unroll
;                 for (int n = 0; n < 4; ++n) acc[m][n] = __builtin_amdgcn_mfma_f32_16x16x32_bf16(b0[n], a0[m], acc[m][n], 0, 0, 0);
;             __builtin_amdgcn_sched_barrier(0);
; #pragma unroll
;             for (int m = 0; m < 4; ++m)
; #pragma unroll
;                 for (int n = 0; n < 4; ++n) acc[m][n] = __builtin_amdgcn_mfma_f32_16x16x32_bf16(b1[n], a1[m], acc[m][n], 0, 0, 0);
;             __builtin_amdgcn_s_setprio(0);
;             __builtin_amdgcn_sched_barrier(0);
;         }
;         asm volatile("s_waitcnt vmcnt(0)" ::: "memory");
;         __syncthreads();
.LBB0_182:
	s_add_i32 s45, s43, 0xffff8000
	s_and_b32 s45, s45, 0x8000
	v_add_u32_e32 v89, s45, v88
	ds_read_b128 v[90:93], v89
	ds_read_b128 v[94:97], v89 offset:2048
	ds_read_b128 v[98:101], v89 offset:4096
	ds_read_b128 v[114:117], v89 offset:6144
	v_or_b32_e32 v89, s45, v87
	ds_read_b128 v[118:121], v89 offset:16384
	ds_read_b128 v[122:125], v89 offset:18432
	ds_read_b128 v[126:129], v89 offset:20480
	ds_read_b128 v[130:133], v89 offset:22528
	v_add_u32_e32 v89, s45, v86
	ds_read_b128 v[134:137], v89
	ds_read_b128 v[138:141], v89 offset:2048
	ds_read_b128 v[142:145], v89 offset:4096
	ds_read_b128 v[146:149], v89 offset:6144
	v_or_b32_e32 v89, s45, v85
	ds_read_b128 v[150:153], v89 offset:16384
	ds_read_b128 v[154:157], v89 offset:18432
	ds_read_b128 v[158:161], v89 offset:20480
	ds_read_b128 v[162:165], v89 offset:22528
	s_setprio 1
	s_waitcnt lgkmcnt(11)
	v_mfma_f32_16x16x32_bf16 v[36:39], v[118:121], v[90:93], v[36:39]
	s_waitcnt lgkmcnt(10)
	v_mfma_f32_16x16x32_bf16 v[24:27], v[122:125], v[90:93], v[24:27]
	s_waitcnt lgkmcnt(9)
	v_mfma_f32_16x16x32_bf16 v[20:23], v[126:129], v[90:93], v[20:23]
	s_waitcnt lgkmcnt(8)
	v_mfma_f32_16x16x32_bf16 v[16:19], v[130:133], v[90:93], v[16:19]
	v_mfma_f32_16x16x32_bf16 v[12:15], v[118:121], v[94:97], v[12:15]
	v_mfma_f32_16x16x32_bf16 v[8:11], v[122:125], v[94:97], v[8:11]
	v_mfma_f32_16x16x32_bf16 v[4:7], v[126:129], v[94:97], v[4:7]
	v_mfma_f32_16x16x32_bf16 v[0:3], v[130:133], v[94:97], v[0:3]
	v_mfma_f32_16x16x32_bf16 v[28:31], v[118:121], v[98:101], v[28:31]
	v_mfma_f32_16x16x32_bf16 v[32:35], v[122:125], v[98:101], v[32:35]
	v_mfma_f32_16x16x32_bf16 v[40:43], v[126:129], v[98:101], v[40:43]
	v_mfma_f32_16x16x32_bf16 v[44:47], v[130:133], v[98:101], v[44:47]
	v_mfma_f32_16x16x32_bf16 v[48:51], v[118:121], v[114:117], v[48:51]
	v_mfma_f32_16x16x32_bf16 v[52:55], v[122:125], v[114:117], v[52:55]
	v_mfma_f32_16x16x32_bf16 v[56:59], v[126:129], v[114:117], v[56:59]
	v_mfma_f32_16x16x32_bf16 v[60:63], v[130:133], v[114:117], v[60:63]
	s_setprio 0
	s_waitcnt lgkmcnt(0)
	s_barrier
	s_cmpk_eq_i32 s0, 0x700
	s_cbranch_scc1 .Lnodma_g182
	s_add_u32 s100, s0, 0x80
	s_addc_u32 s101, s1, 0
	s_add_u32 s99, s98, s45
	s_setprio 1
	v_mfma_f32_16x16x32_bf16 v[36:39], v[150:153], v[134:137], v[36:39]
	v_mfma_f32_16x16x32_bf16 v[24:27], v[154:157], v[134:137], v[24:27]
	s_mov_b32 m0, s99
	v_lshl_add_u64 v[166:167], v[64:65], 0, s[100:101]
	global_load_lds_dwordx4 v[166:167], off
	v_mfma_f32_16x16x32_bf16 v[20:23], v[158:161], v[134:137], v[20:23]
	v_mfma_f32_16x16x32_bf16 v[16:19], v[162:165], v[134:137], v[16:19]
	s_add_u32 m0, s99, 0x4000
	v_lshl_add_u64 v[166:167], v[66:67], 0, s[100:101]
	global_load_lds_dwordx4 v[166:167], off
	v_mfma_f32_16x16x32_bf16 v[12:15], v[150:153], v[138:141], v[12:15]
	v_mfma_f32_16x16x32_bf16 v[8:11], v[154:157], v[138:141], v[8:11]
	s_add_u32 m0, s99, 0x1000
	v_lshl_add_u64 v[166:167], v[68:69], 0, s[100:101]
	global_load_lds_dwordx4 v[166:167], off
	v_mfma_f32_16x16x32_bf16 v[4:7], v[158:161], v[138:141], v[4:7]
	v_mfma_f32_16x16x32_bf16 v[0:3], v[162:165], v[138:141], v[0:3]
	s_add_u32 m0, s99, 0x5000
	v_lshl_add_u64 v[166:167], v[70:71], 0, s[100:101]
	global_load_lds_dwordx4 v[166:167], off
	v_mfma_f32_16x16x32_bf16 v[28:31], v[150:153], v[142:145], v[28:31]
	v_mfma_f32_16x16x32_bf16 v[32:35], v[154:157], v[142:145], v[32:35]
	s_add_u32 m0, s99, 0x2000
	v_lshl_add_u64 v[166:167], v[72:73], 0, s[100:101]
	global_load_lds_dwordx4 v[166:167], off
	v_mfma_f32_16x16x32_bf16 v[40:43], v[158:161], v[142:145], v[40:43]
	v_mfma_f32_16x16x32_bf16 v[44:47], v[162:165], v[142:145], v[44:47]
	s_add_u32 m0, s99, 0x6000
	v_lshl_add_u64 v[166:167], v[74:75], 0, s[100:101]
	global_load_lds_dwordx4 v[166:167], off
	v_mfma_f32_16x16x32_bf16 v[48:51], v[150:153], v[146:149], v[48:51]
	v_mfma_f32_16x16x32_bf16 v[52:55], v[154:157], v[146:149], v[52:55]
	s_add_u32 m0, s99, 0x3000
	v_lshl_add_u64 v[166:167], v[76:77], 0, s[100:101]
	global_load_lds_dwordx4 v[166:167], off
	v_mfma_f32_16x16x32_bf16 v[56:59], v[158:161], v[146:149], v[56:59]
	v_mfma_f32_16x16x32_bf16 v[60:63], v[162:165], v[146:149], v[60:63]
	s_add_u32 m0, s99, 0x7000
	v_lshl_add_u64 v[166:167], v[78:79], 0, s[100:101]
	global_load_lds_dwordx4 v[166:167], off
	s_setprio 0
	s_branch .Ljoin_g182

; __device__ __forceinline__ unsigned pack2bf(float a, float b) { const f32x2 v = {a, b}; return __builtin_bit_cast(unsigned, __builtin_convertvector(v, bf2_t)); }
; __device__ __forceinline__ void attn_unit(const Params& p, int b, int h, int q0, int nkeys, char* smem) {
;     ...
; #pragma unroll
;     for (int qs = 0; qs < 2; ++qs) {
;         float l = lrun[qs]; l += __shfl_xor(l, 16); l += __shfl_xor(l, 32);
;         const float rl = 1.f / l;
;         const size_t row = (size_t)b * TT + q0 + wid * 32 + qs * 16 + fr;
; #pragma unroll
;         for (int dv = 0; dv < 4; ++dv) {
;             uint2 w; w.x = pack2bf(o[dv][qs][0] * rl, o[dv][qs][1] * rl); w.y = pack2bf(o[dv][qs][2] * rl, o[dv][qs][3] * rl);
;             *(uint2*)(Y + row * 1024 + 256 + h * 64 + dv * 16 + fq * 4) = w;
;         }
;     }
.LBB0_447:
	v_add_f32_e32 v118, v118, v119
	v_add_f32_e32 v119, v176, v177
	v_mbcnt_hi_u32_b32 v0, -1, v194
	v_and_b32_e32 v2, 64, v0
	v_xor_b32_e32 v1, 16, v0
	v_add_u32_e32 v2, 64, v2
	v_cmp_lt_i32_e32 vcc, v1, v2
	v_xor_b32_e32 v4, 32, v0
	v_ashrrev_i32_e32 v115, 31, v114
	v_cndmask_b32_e32 v1, v0, v1, vcc
	v_lshlrev_b32_e32 v3, 2, v1
	ds_bpermute_b32 v1, v3, v118
	v_cmp_lt_i32_e32 vcc, v4, v2
	v_mad_u32_u24 v104, s31, v204, v111
	v_mov_b32_e32 v117, v105
	v_cndmask_b32_e32 v0, v0, v4, vcc
	v_lshlrev_b32_e32 v10, 2, v0
	s_waitcnt lgkmcnt(0)
	v_add_f32_e32 v0, v118, v1
	ds_bpermute_b32 v1, v10, v0
	s_waitcnt lgkmcnt(0)
	v_add_f32_e32 v2, v0, v1
	v_div_scale_f32 v4, s[0:1], v2, v2, 1.0
	v_rcp_f32_e32 v5, v4
	v_lshl_add_u64 v[0:1], v[104:105], 0, v[114:115]
	s_lshl_b32 s0, s34, 6
	v_lshlrev_b64 v[0:1], 11, v[0:1]
	v_fma_f32 v6, -v4, v5, 1.0
	v_fmac_f32_e32 v5, v6, v5
	v_div_scale_f32 v6, vcc, 1.0, v2, 1.0
	v_mul_f32_e32 v7, v6, v5
	v_fma_f32 v8, -v4, v7, v6
	v_fmac_f32_e32 v7, v8, v5
	s_ashr_i32 s1, s0, 31
	v_fma_f32 v4, -v4, v7, v6
	v_lshl_add_u64 v[0:1], s[26:27], 0, v[0:1]
	v_div_fmas_f32 v4, v4, v5, v7
	v_lshl_add_u64 v[0:1], s[0:1], 1, v[0:1]
	v_div_fixup_f32 v2, v4, v2, 1.0
	v_lshl_add_u64 v[0:1], v[0:1], 0, v[116:117]
	s_mov_b64 s[0:1], 0x25f3200
	v_lshl_add_u64 v[4:5], v[0:1], 0, s[0:1]
	v_pk_mul_f32 v[6:7], v[92:93], v[2:3] op_sel_hi:[1,0]
	v_pk_mul_f32 v[8:9], v[94:95], v[2:3] op_sel_hi:[1,0]
	s_mov_b32 s0, 0x25f3000
	v_cvt_pk_bf16_f32 v6, v6, v7
	v_cvt_pk_bf16_f32 v7, v8, v9
	v_add_co_u32_e32 v8, vcc, s0, v0
	s_mov_b32 s34, s30
	s_nop 0
	v_addc_co_u32_e32 v9, vcc, 0, v1, vcc
	global_store_dwordx2 v[8:9], v[6:7], off offset:512
	v_pk_mul_f32 v[6:7], v[88:89], v[2:3] op_sel_hi:[1,0]
	v_pk_mul_f32 v[8:9], v[90:91], v[2:3] op_sel_hi:[1,0]
	ds_bpermute_b32 v3, v3, v119
	v_cvt_pk_bf16_f32 v6, v6, v7
	v_cvt_pk_bf16_f32 v7, v8, v9
	global_store_dwordx2 v[4:5], v[6:7], off offset:32
	s_waitcnt lgkmcnt(0)
	v_pk_mul_f32 v[6:7], v[80:81], v[2:3] op_sel_hi:[1,0]
	v_pk_mul_f32 v[8:9], v[82:83], v[2:3] op_sel_hi:[1,0]
	v_add_f32_e32 v3, v119, v3
	ds_bpermute_b32 v10, v10, v3
	v_cvt_pk_bf16_f32 v6, v6, v7
	v_cvt_pk_bf16_f32 v7, v8, v9
	global_store_dwordx2 v[4:5], v[6:7], off offset:64
	v_pk_mul_f32 v[6:7], v[72:73], v[2:3] op_sel_hi:[1,0]
	s_waitcnt lgkmcnt(0)
	v_add_f32_e32 v8, v3, v10
	v_div_scale_f32 v9, s[0:1], v8, v8, 1.0
	v_rcp_f32_e32 v10, v9
	v_pk_mul_f32 v[2:3], v[74:75], v[2:3] op_sel_hi:[1,0]
	v_cvt_pk_bf16_f32 v6, v6, v7
	v_cvt_pk_bf16_f32 v7, v2, v3
	v_fma_f32 v2, -v9, v10, 1.0
	v_fmac_f32_e32 v10, v2, v10
	v_div_scale_f32 v2, vcc, 1.0, v8, 1.0
	v_mul_f32_e32 v3, v2, v10
	global_store_dwordx2 v[4:5], v[6:7], off offset:96
	v_fma_f32 v4, -v9, v3, v2
	v_fmac_f32_e32 v3, v4, v10
	v_fma_f32 v2, -v9, v3, v2
	v_div_fmas_f32 v2, v2, v10, v3
	s_mov_b64 s[0:1], 0x25fb200
	v_div_fixup_f32 v2, v2, v8, 1.0
	v_lshl_add_u64 v[4:5], v[0:1], 0, s[0:1]
	s_mov_b32 s0, 0x25fb000
	v_pk_mul_f32 v[6:7], v[84:85], v[2:3] op_sel_hi:[1,0]
	v_pk_mul_f32 v[8:9], v[86:87], v[2:3] op_sel_hi:[1,0]
	v_add_co_u32_e32 v0, vcc, s0, v0
	v_cvt_pk_bf16_f32 v6, v6, v7
	v_cvt_pk_bf16_f32 v7, v8, v9
	v_addc_co_u32_e32 v1, vcc, 0, v1, vcc
	global_store_dwordx2 v[0:1], v[6:7], off offset:512
	v_pk_mul_f32 v[0:1], v[76:77], v[2:3] op_sel_hi:[1,0]
	v_pk_mul_f32 v[6:7], v[78:79], v[2:3] op_sel_hi:[1,0]
	v_cvt_pk_bf16_f32 v0, v0, v1
	v_cvt_pk_bf16_f32 v1, v6, v7
	global_store_dwordx2 v[4:5], v[0:1], off offset:32
	v_pk_mul_f32 v[0:1], v[68:69], v[2:3] op_sel_hi:[1,0]
	v_pk_mul_f32 v[6:7], v[70:71], v[2:3] op_sel_hi:[1,0]
	v_cvt_pk_bf16_f32 v0, v0, v1
	v_cvt_pk_bf16_f32 v1, v6, v7
	global_store_dwordx2 v[4:5], v[0:1], off offset:64
	v_pk_mul_f32 v[0:1], v[64:65], v[2:3] op_sel_hi:[1,0]
	v_pk_mul_f32 v[2:3], v[66:67], v[2:3] op_sel_hi:[1,0]
	v_cvt_pk_bf16_f32 v0, v0, v1
	v_cvt_pk_bf16_f32 v1, v2, v3
	global_store_dwordx2 v[4:5], v[0:1], off offset:96

; #define LSTOREX(P, st_) { LST1(st_, 0, P##k0) LST1(st_, 1, P##k1) LST1(st_, 2, P##k2) \
;                           *(uint4*)(smem + (st_) + KSZ + vdv * VROW + vcc * 16) = P##v0; *(uint4*)(smem + (st_) + KSZ + (vdv + 32) * VROW + vcc * 16) = P##v1; }
; __device__ __forceinline__ void attn_unit(const Params& p, int b, int h, int q0, int nkeys, char* smem) {
;     ...
;     bf16x8 qf[2][3];
; #pragma unroll
;     for (int qs = 0; qs < 2; ++qs)
; #pragma unroll
;         for (int s = 0; s < 3; ++s) qf[qs][s] = *(const bf16x8*)(Qg + (size_t)(q0 + wid * 32 + qs * 16 + fr) * 96 + s * 32 + fq * 8);
;     f32x4 o[4][2];
; #pragma unroll
;     for (int a = 0; a < 4; ++a)
; #pragma unroll
;         for (int c = 0; c < 2; ++c) o[a][c] = (f32x4){0.f, 0.f, 0.f, 0.f};
;     float lrun[2] = {0.f, 0.f};
;     ...
;     uint4 ak0, ak1, ak2, av0, av1, bk0, bk1, bk2, bv0, bv1;
;     const int vdv = tid >> 3, vcc = tid & 7;
;     ...
;     const int nt = nkeys >> 6;
;     __syncthreads();
;     GLOADX(a, 0)
;     LSTOREX(a, 0)
;     GLOADX(a, 64)
;     __syncthreads();
.LBB0_458:
	s_lshl_b32 s0, s31, 3
	s_add_i32 s46, s34, s0
	v_mov_b32_e32 v64, v109
	s_mul_i32 s44, s46, 0xcc000
	v_readlane_b32 s0, v251, 56
	s_mul_hi_i32 s42, s46, 0xcc000
	v_and_b32_e32 v72, 15, v64
	v_bfe_u32 v28, v64, 4, 2
	v_readlane_b32 s1, v251, 57
	s_add_u32 s0, s0, s44
	v_ashrrev_i32_e32 v0, 1, v64
	s_addc_u32 s1, s1, s42
	v_readlane_b32 s4, v251, 58
	v_and_b32_e32 v114, 0xffffffe0, v0
	v_add_u32_e32 v111, s43, v72
	v_lshlrev_b32_e32 v104, 4, v28
	s_add_u32 s44, s4, s44
	v_add_u32_e32 v12, v111, v114
	s_waitcnt vmcnt(0)
	v_lshl_add_u64 v[8:9], s[0:1], 0, v[104:105]
	s_movk_i32 s4, 0xc0
	v_readlane_b32 s5, v251, 59
	v_mad_i64_i32 v[10:11], s[0:1], v12, s4, v[8:9]
	v_add_u32_e32 v12, 16, v12
	v_ashrrev_i32_e32 v65, 31, v64
	s_addc_u32 s45, s5, s42
	v_mad_i64_i32 v[20:21], s[0:1], v12, s4, v[8:9]
	v_lshlrev_b64 v[66:67], 4, v[64:65]
	s_mul_i32 s47, s46, 0x88000
	v_readlane_b32 s0, v251, 60
	v_lshl_add_u64 v[24:25], s[44:45], 0, v[66:67]
	s_movk_i32 s4, 0x2000
	s_mul_hi_i32 s42, s46, 0x88000
	s_add_u32 s0, s0, s47
	v_readlane_b32 s1, v251, 61
	v_add_co_u32_e32 v26, vcc, s4, v24
	global_load_dwordx4 v[0:3], v[10:11], off
	global_load_dwordx4 v[4:7], v[10:11], off offset:64
	s_nop 0
	global_load_dwordx4 v[8:11], v[10:11], off offset:128
	s_nop 0
	global_load_dwordx4 v[12:15], v[20:21], off
	global_load_dwordx4 v[16:19], v[20:21], off offset:64
	s_nop 0
	global_load_dwordx4 v[20:23], v[20:21], off offset:128
	s_barrier
	global_load_dwordx4 v[44:47], v[24:25], off
	s_addc_u32 s1, s1, s42
	v_addc_co_u32_e32 v27, vcc, 0, v25, vcc
	v_ashrrev_i32_e32 v65, 3, v64
	global_load_dwordx4 v[48:51], v[26:27], off offset:-4096
	global_load_dwordx4 v[52:55], v[26:27], off
	v_mov_b64_e32 v[26:27], s[0:1]
	s_movk_i32 s4, 0x2200
	v_lshlrev_b32_e32 v29, 4, v64
	v_mad_i64_i32 v[26:27], s[0:1], v65, s4, v[26:27]
	v_and_b32_e32 v68, 0x70, v29
	v_mov_b32_e32 v69, v105
	v_lshl_add_u64 v[32:33], v[26:27], 0, v[68:69]
	s_mov_b32 s0, 0x44000
	v_add_co_u32_e32 v40, vcc, s0, v32
	s_movk_i32 s0, 0x4000
	s_nop 0
	v_addc_co_u32_e32 v41, vcc, 0, v33, vcc
	v_lshlrev_b32_e32 v116, 3, v28
	v_add_co_u32_e32 v28, vcc, s0, v24
	s_movk_i32 s0, 0x5000
	s_nop 0
	v_addc_co_u32_e32 v29, vcc, 0, v25, vcc
	v_add_co_u32_e32 v36, vcc, s0, v24
	global_load_dwordx4 v[56:59], v[32:33], off
	global_load_dwordx4 v[60:63], v[40:41], off
	v_addc_co_u32_e32 v37, vcc, 0, v25, vcc
	global_load_dwordx4 v[24:27], v[28:29], off offset:-4096
	s_nop 0
	global_load_dwordx4 v[28:31], v[28:29], off
	s_nop 0
	global_load_dwordx4 v[32:35], v[32:33], off offset:128
	s_nop 0
	global_load_dwordx4 v[36:39], v[36:37], off
	s_nop 0
	global_load_dwordx4 v[40:43], v[40:41], off offset:128
	s_mov_b32 s5, 0x2aaaaaab
	v_mul_hi_i32 v69, v64, s5
	v_lshrrev_b32_e32 v74, 31, v69
	v_ashrrev_i32_e32 v69, 1, v69
	v_mad_i64_i32 v[70:71], s[0:1], v65, s4, 0
	v_add_u32_e32 v69, v69, v74
	v_mul_lo_u32 v76, v69, -12
	s_movk_i32 s0, 0xd0
	v_add_u32_e32 v73, 0x100, v64
	v_mul_lo_u32 v69, v69, s0
	v_add_lshl_u32 v76, v76, v64, 4
	v_mul_hi_i32 v75, v73, s5
	v_add_u32_e32 v115, v69, v76
	v_lshrrev_b32_e32 v74, 31, v75
	v_mov_b32_e32 v92, 0
	s_mov_b32 s42, 3
	v_mov_b32_e32 v93, v92
	v_mov_b32_e32 v94, v92
	v_mov_b32_e32 v95, v92
	v_mov_b32_e32 v84, v92
	v_mov_b32_e32 v85, v92
	v_mov_b32_e32 v86, v92
	v_mov_b32_e32 v87, v92
	v_mov_b32_e32 v88, v92
	v_mov_b32_e32 v89, v92
	v_mov_b32_e32 v90, v92
	v_mov_b32_e32 v91, v92
	v_mov_b32_e32 v76, v92
	v_mov_b32_e32 v77, v92
	v_mov_b32_e32 v78, v92
	v_mov_b32_e32 v79, v92
	v_mov_b32_e32 v80, v92
	v_mov_b32_e32 v81, v92
	v_mov_b32_e32 v82, v92
	v_mov_b32_e32 v83, v92
	v_mov_b32_e32 v69, v92
	v_mov_b32_e32 v118, v92
	v_mov_b32_e32 v119, v92
	s_waitcnt vmcnt(9)
	ds_write_b128 v115, v[44:47]
	v_ashrrev_i32_e32 v44, 1, v75
	v_add_u32_e32 v44, v44, v74
	v_mul_lo_u32 v45, v44, -12
	v_mul_lo_u32 v44, v44, s0
	v_add_lshl_u32 v45, v45, v73, 4
	v_add_u32_e32 v117, v44, v45
	v_add_u32_e32 v44, 0x200, v64
	v_mul_hi_i32 v45, v44, s5
	v_lshrrev_b32_e32 v46, 31, v45
	v_ashrrev_i32_e32 v45, 1, v45
	v_add_u32_e32 v45, v45, v46
	v_mul_lo_u32 v46, v45, -12
	v_mul_lo_u32 v45, v45, s0
	v_add_lshl_u32 v44, v46, v44, 4
	s_movk_i32 s0, 0x90
	v_add_u32_e32 v217, v45, v44
	v_mul_lo_u32 v44, v65, s0
	v_add_u32_e32 v218, v44, v68
	v_sub_u32_e32 v44, v104, v116
	v_mul_u32_u24_e32 v45, 0xd0, v72
	v_mul_u32_u24_e32 v46, 0x90, v72
	v_mad_i64_i32 v[120:121], s[0:1], s46, v200, v[70:71]
	v_or_b32_e32 v120, v120, v68
	v_mad_i64_i32 v[122:123], s[0:1], s46, v203, v[66:67]
	v_add_u32_e32 v104, v104, v45
	v_add_u32_e32 v219, v44, v46
	v_mov_b32_e32 v68, v92
	v_mov_b32_e32 v70, v92
	v_mov_b32_e32 v71, v92
	v_mov_b32_e32 v72, v92
	v_mov_b32_e32 v73, v92
	v_mov_b32_e32 v74, v92
	v_mov_b32_e32 v75, v92
	v_mov_b32_e32 v64, v92
	v_mov_b32_e32 v65, v92
	v_mov_b32_e32 v66, v92
	v_mov_b32_e32 v67, v92
	s_waitcnt vmcnt(8)
	ds_write_b128 v117, v[48:51]
	s_waitcnt vmcnt(7)
	ds_write_b128 v217, v[52:55]
	s_waitcnt vmcnt(6)
	ds_write_b128 v218, v[56:59] offset:13312
	s_waitcnt vmcnt(5)
	ds_write_b128 v218, v[60:63] offset:17920
	s_waitcnt lgkmcnt(0)
	s_barrier
	v_add_u32_e32 v178, 0x3400, v219
	v_add_u32_e32 v179, 0x3d00, v219
	v_add_u32_e32 v191, 0x4600, v219
	v_add_u32_e32 v208, 0x4f00, v219
	v_add_u32_e32 v209, 0x8c00, v219
	v_add_u32_e32 v210, 0x9500, v219
	v_add_u32_e32 v211, 0x9e00, v219
	v_add_u32_e32 v212, 0xa700, v219
	v_mov_b32_e32 v176, 0
	v_mov_b32_e32 v177, 0
	s_branch .LBB0_460

.LBB0_462:
	s_setprio 1
	v_readlane_b32 s4, v253, 31
	v_readlane_b32 s6, v253, 33
	v_readlane_b32 s7, v253, 34
	v_readlane_b32 s5, v253, 32
	ds_read_b128 v[160:163], v104 offset:0
	ds_read_b128 v[164:167], v104 offset:3328
	ds_read_b128 v[168:171], v104 offset:6656
	ds_read_b128 v[172:175], v104 offset:9984
	ds_read_b128 v[224:227], v104 offset:64
	ds_read_b128 v[228:231], v104 offset:3392
	ds_read_b128 v[232:235], v104 offset:6720
	ds_read_b128 v[236:239], v104 offset:10048
	s_waitcnt lgkmcnt(6)
	v_mfma_f32_16x16x32_bf16 v[124:127], v[160:163], v[0:3], -4.0
	v_mfma_f32_16x16x32_bf16 v[128:131], v[160:163], v[12:15], -4.0
	ds_read_b128 v[160:163], v104 offset:128
	v_mfma_f32_16x16x32_bf16 v[132:135], v[164:167], v[0:3], -4.0
	v_mfma_f32_16x16x32_bf16 v[136:139], v[164:167], v[12:15], -4.0
	ds_read_b128 v[164:167], v104 offset:3456
	s_waitcnt lgkmcnt(6)
	v_mfma_f32_16x16x32_bf16 v[140:143], v[168:171], v[0:3], -4.0
	v_mfma_f32_16x16x32_bf16 v[144:147], v[168:171], v[12:15], -4.0
	ds_read_b128 v[168:171], v104 offset:6784
	v_mfma_f32_16x16x32_bf16 v[148:151], v[172:175], v[0:3], -4.0
	v_mfma_f32_16x16x32_bf16 v[152:155], v[172:175], v[12:15], -4.0
	ds_read_b128 v[172:175], v104 offset:10112
	s_waitcnt lgkmcnt(6)
	v_mfma_f32_16x16x32_bf16 v[124:127], v[224:227], v[4:7], v[124:127]
	v_mfma_f32_16x16x32_bf16 v[128:131], v[224:227], v[16:19], v[128:131]
	ds_read_b64 v[224:225], v219 offset:13312
	ds_read_b64 v[226:227], v219 offset:13344
	v_mfma_f32_16x16x32_bf16 v[132:135], v[228:231], v[4:7], v[132:135]
	v_mfma_f32_16x16x32_bf16 v[136:139], v[228:231], v[16:19], v[136:139]
	ds_read_b64 v[228:229], v219 offset:15616
	ds_read_b64 v[230:231], v219 offset:15648
	s_waitcnt lgkmcnt(8)
	v_mfma_f32_16x16x32_bf16 v[140:143], v[232:235], v[4:7], v[140:143]
	v_mfma_f32_16x16x32_bf16 v[144:147], v[232:235], v[16:19], v[144:147]
	ds_read_b64 v[232:233], v219 offset:17920
	ds_read_b64 v[234:235], v219 offset:17952
	v_mfma_f32_16x16x32_bf16 v[148:151], v[236:239], v[4:7], v[148:151]
	v_mfma_f32_16x16x32_bf16 v[152:155], v[236:239], v[16:19], v[152:155]
	ds_read_b64 v[236:237], v219 offset:20224
	ds_read_b64 v[238:239], v219 offset:20256
	s_waitcnt lgkmcnt(10)
	v_mfma_f32_16x16x32_bf16 v[124:127], v[160:163], v[8:11], v[124:127]
	v_mfma_f32_16x16x32_bf16 v[128:131], v[160:163], v[20:23], v[128:131]
	ds_read_b64 v[160:161], v219 offset:13376
	ds_read_b64 v[162:163], v219 offset:13408
	v_mfma_f32_16x16x32_bf16 v[132:135], v[164:167], v[8:11], v[132:135]
	v_mfma_f32_16x16x32_bf16 v[136:139], v[164:167], v[20:23], v[136:139]
	ds_read_b64 v[164:165], v219 offset:15680
	ds_read_b64 v[166:167], v219 offset:15712
	s_waitcnt lgkmcnt(12)
	v_mfma_f32_16x16x32_bf16 v[140:143], v[168:171], v[8:11], v[140:143]
	v_mfma_f32_16x16x32_bf16 v[144:147], v[168:171], v[20:23], v[144:147]
	ds_read_b64 v[168:169], v219 offset:17984
	ds_read_b64 v[170:171], v219 offset:18016
	v_mfma_f32_16x16x32_bf16 v[148:151], v[172:175], v[8:11], v[148:151]
	v_mfma_f32_16x16x32_bf16 v[152:155], v[172:175], v[20:23], v[152:155]
	ds_read_b64 v[172:173], v219 offset:20288
	ds_read_b64 v[174:175], v219 offset:20320
	s_setprio 0
	v_exp_f32_e32 v124, v124
	v_exp_f32_e32 v125, v125
	v_exp_f32_e32 v126, v126
	v_exp_f32_e32 v127, v127
	v_add_f32_e32 v118, v118, v124
	v_add_f32_e32 v119, v119, v125
	v_exp_f32_e32 v128, v128
	v_exp_f32_e32 v129, v129
	v_add_f32_e32 v118, v118, v126
	v_add_f32_e32 v119, v119, v127
	v_exp_f32_e32 v130, v130
	v_exp_f32_e32 v131, v131
	v_add_f32_e32 v176, v176, v128
	v_add_f32_e32 v177, v177, v129
	v_exp_f32_e32 v132, v132
	v_exp_f32_e32 v133, v133
	v_add_f32_e32 v176, v176, v130
	v_add_f32_e32 v177, v177, v131
	v_exp_f32_e32 v134, v134
	v_exp_f32_e32 v135, v135
	v_add_f32_e32 v118, v118, v132
	v_add_f32_e32 v119, v119, v133
	v_exp_f32_e32 v136, v136
	v_exp_f32_e32 v137, v137
	v_add_f32_e32 v118, v118, v134
	v_add_f32_e32 v119, v119, v135
	v_exp_f32_e32 v138, v138
	v_exp_f32_e32 v139, v139
	v_add_f32_e32 v176, v176, v136
	v_add_f32_e32 v177, v177, v137
	v_cvt_pk_bf16_f32 v240, v124, v125
	v_add_f32_e32 v176, v176, v138
	v_add_f32_e32 v177, v177, v139
	v_cvt_pk_bf16_f32 v241, v126, v127
	v_cvt_pk_bf16_f32 v242, v132, v133
	v_cvt_pk_bf16_f32 v243, v134, v135
	v_cvt_pk_bf16_f32 v244, v128, v129
	v_cvt_pk_bf16_f32 v245, v130, v131
	v_cvt_pk_bf16_f32 v246, v136, v137
	v_cvt_pk_bf16_f32 v247, v138, v139
	s_waitcnt lgkmcnt(12)
	v_mfma_f32_16x16x32_bf16 v[92:95], v[224:227], v[240:243], v[92:95]
	v_exp_f32_e32 v140, v140
	v_exp_f32_e32 v141, v141
	v_exp_f32_e32 v142, v142
	v_exp_f32_e32 v143, v143
	v_add_f32_e32 v118, v118, v140
	v_mfma_f32_16x16x32_bf16 v[84:87], v[224:227], v[244:247], v[84:87]
	v_add_f32_e32 v119, v119, v141
	v_exp_f32_e32 v144, v144
	v_exp_f32_e32 v145, v145
	v_add_f32_e32 v118, v118, v142
	v_add_f32_e32 v119, v119, v143
	v_mfma_f32_16x16x32_bf16 v[88:91], v[228:231], v[240:243], v[88:91]
	v_exp_f32_e32 v146, v146
	v_exp_f32_e32 v147, v147
	v_add_f32_e32 v176, v176, v144
	v_add_f32_e32 v177, v177, v145
	v_exp_f32_e32 v148, v148
	v_mfma_f32_16x16x32_bf16 v[76:79], v[228:231], v[244:247], v[76:79]
	v_exp_f32_e32 v149, v149
	v_add_f32_e32 v176, v176, v146
	v_add_f32_e32 v177, v177, v147
	v_exp_f32_e32 v150, v150
	v_exp_f32_e32 v151, v151
	s_waitcnt lgkmcnt(8)
	v_mfma_f32_16x16x32_bf16 v[80:83], v[232:235], v[240:243], v[80:83]
	v_add_f32_e32 v118, v118, v148
	v_add_f32_e32 v119, v119, v149
	v_exp_f32_e32 v152, v152
	v_exp_f32_e32 v153, v153
	v_add_f32_e32 v118, v118, v150
	v_mfma_f32_16x16x32_bf16 v[68:71], v[232:235], v[244:247], v[68:71]
	v_add_f32_e32 v119, v119, v151
	v_exp_f32_e32 v154, v154
	v_exp_f32_e32 v155, v155
	v_add_f32_e32 v176, v176, v152
	v_add_f32_e32 v177, v177, v153
	v_mfma_f32_16x16x32_bf16 v[72:75], v[236:239], v[240:243], v[72:75]
	v_cvt_pk_bf16_f32 v96, v140, v141
	v_add_f32_e32 v176, v176, v154
	v_add_f32_e32 v177, v177, v155
	v_cvt_pk_bf16_f32 v97, v142, v143
	v_cvt_pk_bf16_f32 v98, v148, v149
	v_mfma_f32_16x16x32_bf16 v[64:67], v[236:239], v[244:247], v[64:67]
	v_cvt_pk_bf16_f32 v99, v150, v151
	v_cvt_pk_bf16_f32 v100, v144, v145
	v_cvt_pk_bf16_f32 v101, v146, v147
	v_cvt_pk_bf16_f32 v102, v152, v153
	v_cvt_pk_bf16_f32 v103, v154, v155
	s_nop 1
	s_waitcnt lgkmcnt(4)
	v_mfma_f32_16x16x32_bf16 v[92:95], v[160:163], v[96:99], v[92:95]
	v_mfma_f32_16x16x32_bf16 v[84:87], v[160:163], v[100:103], v[84:87]
	v_mfma_f32_16x16x32_bf16 v[88:91], v[164:167], v[96:99], v[88:91]
	v_mfma_f32_16x16x32_bf16 v[76:79], v[164:167], v[100:103], v[76:79]
	s_waitcnt lgkmcnt(0)
	v_mfma_f32_16x16x32_bf16 v[80:83], v[168:171], v[96:99], v[80:83]
	v_mfma_f32_16x16x32_bf16 v[68:71], v[168:171], v[100:103], v[68:71]
	v_mfma_f32_16x16x32_bf16 v[72:75], v[172:175], v[96:99], v[72:75]
	v_mfma_f32_16x16x32_bf16 v[64:67], v[172:175], v[100:103], v[64:67]
	s_add_i32 s44, s42, -2
	s_cmp_ge_u32 s44, s35
	s_cbranch_scc1 .LBB0_464
	s_waitcnt vmcnt(4)
	ds_write_b128 v115, v[24:27] offset:22528
	s_waitcnt vmcnt(3)
	ds_write_b128 v117, v[28:31] offset:22528
	s_waitcnt vmcnt(1)
	ds_write_b128 v217, v[36:39] offset:22528
	ds_write_b128 v218, v[32:35] offset:35840
	s_waitcnt vmcnt(0)
	ds_write_b128 v218, v[40:43] offset:40448

.LBB0_466:
	s_setprio 1
	v_readlane_b32 s4, v253, 31
	v_readlane_b32 s6, v253, 33
	v_readlane_b32 s7, v253, 34
	v_readlane_b32 s5, v253, 32
	ds_read_b128 v[160:163], v104 offset:22528
	ds_read_b128 v[164:167], v104 offset:25856
	ds_read_b128 v[168:171], v104 offset:29184
	ds_read_b128 v[172:175], v104 offset:32512
	ds_read_b128 v[224:227], v104 offset:22592
	ds_read_b128 v[228:231], v104 offset:25920
	ds_read_b128 v[232:235], v104 offset:29248
	ds_read_b128 v[236:239], v104 offset:32576
	s_waitcnt lgkmcnt(6)
	v_mfma_f32_16x16x32_bf16 v[124:127], v[160:163], v[0:3], -4.0
	v_mfma_f32_16x16x32_bf16 v[128:131], v[160:163], v[12:15], -4.0
	ds_read_b128 v[160:163], v104 offset:22656
	v_mfma_f32_16x16x32_bf16 v[132:135], v[164:167], v[0:3], -4.0
	v_mfma_f32_16x16x32_bf16 v[136:139], v[164:167], v[12:15], -4.0
	ds_read_b128 v[164:167], v104 offset:25984
	s_waitcnt lgkmcnt(6)
	v_mfma_f32_16x16x32_bf16 v[140:143], v[168:171], v[0:3], -4.0
	v_mfma_f32_16x16x32_bf16 v[144:147], v[168:171], v[12:15], -4.0
	ds_read_b128 v[168:171], v104 offset:29312
	v_mfma_f32_16x16x32_bf16 v[148:151], v[172:175], v[0:3], -4.0
	v_mfma_f32_16x16x32_bf16 v[152:155], v[172:175], v[12:15], -4.0
	ds_read_b128 v[172:175], v104 offset:32640
	s_waitcnt lgkmcnt(6)
	v_mfma_f32_16x16x32_bf16 v[124:127], v[224:227], v[4:7], v[124:127]
	v_mfma_f32_16x16x32_bf16 v[128:131], v[224:227], v[16:19], v[128:131]
	ds_read_b64 v[224:225], v219 offset:35840
	ds_read_b64 v[226:227], v219 offset:35872
	v_mfma_f32_16x16x32_bf16 v[132:135], v[228:231], v[4:7], v[132:135]
	v_mfma_f32_16x16x32_bf16 v[136:139], v[228:231], v[16:19], v[136:139]
	ds_read_b64 v[228:229], v219 offset:38144
	ds_read_b64 v[230:231], v219 offset:38176
	s_waitcnt lgkmcnt(8)
	v_mfma_f32_16x16x32_bf16 v[140:143], v[232:235], v[4:7], v[140:143]
	v_mfma_f32_16x16x32_bf16 v[144:147], v[232:235], v[16:19], v[144:147]
	ds_read_b64 v[232:233], v219 offset:40448
	ds_read_b64 v[234:235], v219 offset:40480
	v_mfma_f32_16x16x32_bf16 v[148:151], v[236:239], v[4:7], v[148:151]
	v_mfma_f32_16x16x32_bf16 v[152:155], v[236:239], v[16:19], v[152:155]
	ds_read_b64 v[236:237], v219 offset:42752
	ds_read_b64 v[238:239], v219 offset:42784
	s_waitcnt lgkmcnt(10)
	v_mfma_f32_16x16x32_bf16 v[124:127], v[160:163], v[8:11], v[124:127]
	v_mfma_f32_16x16x32_bf16 v[128:131], v[160:163], v[20:23], v[128:131]
	ds_read_b64 v[160:161], v219 offset:35904
	ds_read_b64 v[162:163], v219 offset:35936
	v_mfma_f32_16x16x32_bf16 v[132:135], v[164:167], v[8:11], v[132:135]
	v_mfma_f32_16x16x32_bf16 v[136:139], v[164:167], v[20:23], v[136:139]
	ds_read_b64 v[164:165], v219 offset:38208
	ds_read_b64 v[166:167], v219 offset:38240
	s_waitcnt lgkmcnt(12)
	v_mfma_f32_16x16x32_bf16 v[140:143], v[168:171], v[8:11], v[140:143]
	v_mfma_f32_16x16x32_bf16 v[144:147], v[168:171], v[20:23], v[144:147]
	ds_read_b64 v[168:169], v219 offset:40512
	ds_read_b64 v[170:171], v219 offset:40544
	v_mfma_f32_16x16x32_bf16 v[148:151], v[172:175], v[8:11], v[148:151]
	v_mfma_f32_16x16x32_bf16 v[152:155], v[172:175], v[20:23], v[152:155]
	ds_read_b64 v[172:173], v219 offset:42816
	ds_read_b64 v[174:175], v219 offset:42848
	s_setprio 0
	v_exp_f32_e32 v124, v124
	v_exp_f32_e32 v125, v125
	v_exp_f32_e32 v126, v126
	v_exp_f32_e32 v127, v127
	v_add_f32_e32 v118, v118, v124
	v_add_f32_e32 v119, v119, v125
	v_exp_f32_e32 v128, v128
	v_exp_f32_e32 v129, v129
	v_add_f32_e32 v118, v118, v126
	v_add_f32_e32 v119, v119, v127
	v_exp_f32_e32 v130, v130
	v_exp_f32_e32 v131, v131
	v_add_f32_e32 v176, v176, v128
	v_add_f32_e32 v177, v177, v129
	v_exp_f32_e32 v132, v132
	v_exp_f32_e32 v133, v133
	v_add_f32_e32 v176, v176, v130
	v_add_f32_e32 v177, v177, v131
	v_exp_f32_e32 v134, v134
	v_exp_f32_e32 v135, v135
	v_add_f32_e32 v118, v118, v132
	v_add_f32_e32 v119, v119, v133
	v_exp_f32_e32 v136, v136
	v_exp_f32_e32 v137, v137
	v_add_f32_e32 v118, v118, v134
	v_add_f32_e32 v119, v119, v135
	v_exp_f32_e32 v138, v138
	v_exp_f32_e32 v139, v139
	v_add_f32_e32 v176, v176, v136
	v_add_f32_e32 v177, v177, v137
	v_cvt_pk_bf16_f32 v240, v124, v125
	v_add_f32_e32 v176, v176, v138
	v_add_f32_e32 v177, v177, v139
	v_cvt_pk_bf16_f32 v241, v126, v127
	v_cvt_pk_bf16_f32 v242, v132, v133
	v_cvt_pk_bf16_f32 v243, v134, v135
	v_cvt_pk_bf16_f32 v244, v128, v129
	v_cvt_pk_bf16_f32 v245, v130, v131
	v_cvt_pk_bf16_f32 v246, v136, v137
	v_cvt_pk_bf16_f32 v247, v138, v139
	s_waitcnt lgkmcnt(12)
	v_mfma_f32_16x16x32_bf16 v[92:95], v[224:227], v[240:243], v[92:95]
	v_exp_f32_e32 v140, v140
	v_exp_f32_e32 v141, v141
	v_exp_f32_e32 v142, v142
	v_exp_f32_e32 v143, v143
	v_add_f32_e32 v118, v118, v140
	v_mfma_f32_16x16x32_bf16 v[84:87], v[224:227], v[244:247], v[84:87]
	v_add_f32_e32 v119, v119, v141
	v_exp_f32_e32 v144, v144
	v_exp_f32_e32 v145, v145
	v_add_f32_e32 v118, v118, v142
	v_add_f32_e32 v119, v119, v143
	v_mfma_f32_16x16x32_bf16 v[88:91], v[228:231], v[240:243], v[88:91]
	v_exp_f32_e32 v146, v146
	v_exp_f32_e32 v147, v147
	v_add_f32_e32 v176, v176, v144
	v_add_f32_e32 v177, v177, v145
	v_exp_f32_e32 v148, v148
	v_mfma_f32_16x16x32_bf16 v[76:79], v[228:231], v[244:247], v[76:79]
	v_exp_f32_e32 v149, v149
	v_add_f32_e32 v176, v176, v146
	v_add_f32_e32 v177, v177, v147
	v_exp_f32_e32 v150, v150
	v_exp_f32_e32 v151, v151
	s_waitcnt lgkmcnt(8)
	v_mfma_f32_16x16x32_bf16 v[80:83], v[232:235], v[240:243], v[80:83]
	v_add_f32_e32 v118, v118, v148
	v_add_f32_e32 v119, v119, v149
	v_exp_f32_e32 v152, v152
	v_exp_f32_e32 v153, v153
	v_add_f32_e32 v118, v118, v150
	v_mfma_f32_16x16x32_bf16 v[68:71], v[232:235], v[244:247], v[68:71]
	v_add_f32_e32 v119, v119, v151
	v_exp_f32_e32 v154, v154
	v_exp_f32_e32 v155, v155
	v_add_f32_e32 v176, v176, v152
	v_add_f32_e32 v177, v177, v153
	v_mfma_f32_16x16x32_bf16 v[72:75], v[236:239], v[240:243], v[72:75]
	v_cvt_pk_bf16_f32 v96, v140, v141
	v_add_f32_e32 v176, v176, v154
	v_add_f32_e32 v177, v177, v155
	v_cvt_pk_bf16_f32 v97, v142, v143
	v_cvt_pk_bf16_f32 v98, v148, v149
	v_mfma_f32_16x16x32_bf16 v[64:67], v[236:239], v[244:247], v[64:67]
	v_cvt_pk_bf16_f32 v99, v150, v151
	v_cvt_pk_bf16_f32 v100, v144, v145
	v_cvt_pk_bf16_f32 v101, v146, v147
	v_cvt_pk_bf16_f32 v102, v152, v153
	v_cvt_pk_bf16_f32 v103, v154, v155
	s_nop 1
	s_waitcnt lgkmcnt(4)
	v_mfma_f32_16x16x32_bf16 v[92:95], v[160:163], v[96:99], v[92:95]
	v_mfma_f32_16x16x32_bf16 v[84:87], v[160:163], v[100:103], v[84:87]
	v_mfma_f32_16x16x32_bf16 v[88:91], v[164:167], v[96:99], v[88:91]
	v_mfma_f32_16x16x32_bf16 v[76:79], v[164:167], v[100:103], v[76:79]
	s_waitcnt lgkmcnt(0)
	v_mfma_f32_16x16x32_bf16 v[80:83], v[168:171], v[96:99], v[80:83]
	v_mfma_f32_16x16x32_bf16 v[68:71], v[168:171], v[100:103], v[68:71]
	v_mfma_f32_16x16x32_bf16 v[72:75], v[172:175], v[96:99], v[72:75]
	v_mfma_f32_16x16x32_bf16 v[64:67], v[172:175], v[100:103], v[64:67]
	s_andn2_b64 vcc, exec, s[0:1]
	s_cbranch_vccnz .LBB0_459
	s_waitcnt vmcnt(4)
	ds_write_b128 v115, v[44:47]
	s_waitcnt vmcnt(3)
	ds_write_b128 v117, v[48:51]
	s_waitcnt vmcnt(2)
	ds_write_b128 v217, v[52:55]
	s_waitcnt vmcnt(1)
	ds_write_b128 v218, v[56:59] offset:13312
	s_waitcnt vmcnt(0)
	ds_write_b128 v218, v[60:63] offset:17920
	s_branch .LBB0_459

; template <class Epi>
; __device__ __forceinline__ void gemm_tile(const bf16_t* A, int lda, const bf16_t* Bt, int ldb, int K, int m0, int n0, const Epi& epi, char* smem) {
;     ...
;     for (int kt = 0; kt < nk; ++kt) {
;         const int st = (kt & 1) * 32768;
;         if (kt + 1 < nk) G_ISSUE(((kt + 1) & 1) * 32768, (kt + 1) * 64)
;         {
;             bf16x8 a0[4], b0[4], a1[4], b1[4];
;             const int ch0 = ((0 + fq) ^ rsw) << 4, ch1 = ((4 + fq) ^ rsw) << 4;
; #pragma unroll
;             for (int m = 0; m < 4; ++m) a0[m] = *(const bf16x8*)(smem + st + aofs + m * 2048 + ch0);
; #pragma unroll
;             for (int n = 0; n < 4; ++n) b0[n] = *(const bf16x8*)(smem + st + bofs + n * 2048 + ch0);
;             __builtin_amdgcn_sched_barrier(0);
; #pragma unroll
;             for (int m = 0; m < 4; ++m) a1[m] = *(const bf16x8*)(smem + st + aofs + m * 2048 + ch1);
; #pragma unroll
;             for (int n = 0; n < 4; ++n) b1[n] = *(const bf16x8*)(smem + st + bofs + n * 2048 + ch1);
;             __builtin_amdgcn_sched_barrier(0);
;             __builtin_amdgcn_s_setprio(1);
; #pragma unroll
;             for (int m = 0; m < 4; ++m)
; #pragma unroll
;                 for (int n = 0; n < 4; ++n) acc[m][n] = __builtin_amdgcn_mfma_f32_16x16x32_bf16(b0[n], a0[m], acc[m][n], 0, 0, 0);
;             __builtin_amdgcn_sched_barrier(0);
; #pragma unroll
;             for (int m = 0; m < 4; ++m)
; #pragma unroll
;                 for (int n = 0; n < 4; ++n) acc[m][n] = __builtin_amdgcn_mfma_f32_16x16x32_bf16(b1[n], a1[m], acc[m][n], 0, 0, 0);
;             __builtin_amdgcn_s_setprio(0);
;             __builtin_amdgcn_sched_barrier(0);
;         }
;         asm volatile("s_waitcnt vmcnt(0)" ::: "memory");
;         __syncthreads();
.LBB0_697:
	s_add_i32 s34, s31, 0xffff8000
	s_and_b32 s34, s34, 0x8000
	v_add_u32_e32 v102, s34, v88
	ds_read_b128 v[90:93], v102
	ds_read_b128 v[94:97], v102 offset:2048
	ds_read_b128 v[98:101], v102 offset:4096
	ds_read_b128 v[114:117], v102 offset:6144
	v_or_b32_e32 v102, s34, v89
	ds_read_b128 v[118:121], v102 offset:16384
	ds_read_b128 v[122:125], v102 offset:18432
	ds_read_b128 v[126:129], v102 offset:20480
	ds_read_b128 v[130:133], v102 offset:22528
	v_add_u32_e32 v102, s34, v87
	ds_read_b128 v[134:137], v102
	ds_read_b128 v[138:141], v102 offset:2048
	ds_read_b128 v[142:145], v102 offset:4096
	ds_read_b128 v[146:149], v102 offset:6144
	v_or_b32_e32 v102, s34, v86
	ds_read_b128 v[150:153], v102 offset:16384
	ds_read_b128 v[154:157], v102 offset:18432
	ds_read_b128 v[158:161], v102 offset:20480
	ds_read_b128 v[162:165], v102 offset:22528
	s_setprio 1
	s_waitcnt lgkmcnt(11)
	v_mfma_f32_16x16x32_bf16 v[36:39], v[118:121], v[90:93], v[36:39]
	s_waitcnt lgkmcnt(10)
	v_mfma_f32_16x16x32_bf16 v[24:27], v[122:125], v[90:93], v[24:27]
	s_waitcnt lgkmcnt(9)
	v_mfma_f32_16x16x32_bf16 v[20:23], v[126:129], v[90:93], v[20:23]
	s_waitcnt lgkmcnt(8)
	v_mfma_f32_16x16x32_bf16 v[16:19], v[130:133], v[90:93], v[16:19]
	v_mfma_f32_16x16x32_bf16 v[12:15], v[118:121], v[94:97], v[12:15]
	v_mfma_f32_16x16x32_bf16 v[8:11], v[122:125], v[94:97], v[8:11]
	v_mfma_f32_16x16x32_bf16 v[4:7], v[126:129], v[94:97], v[4:7]
	v_mfma_f32_16x16x32_bf16 v[0:3], v[130:133], v[94:97], v[0:3]
	v_mfma_f32_16x16x32_bf16 v[28:31], v[118:121], v[98:101], v[28:31]
	v_mfma_f32_16x16x32_bf16 v[32:35], v[122:125], v[98:101], v[32:35]
	v_mfma_f32_16x16x32_bf16 v[40:43], v[126:129], v[98:101], v[40:43]
	v_mfma_f32_16x16x32_bf16 v[44:47], v[130:133], v[98:101], v[44:47]
	v_mfma_f32_16x16x32_bf16 v[48:51], v[118:121], v[114:117], v[48:51]
	v_mfma_f32_16x16x32_bf16 v[52:55], v[122:125], v[114:117], v[52:55]
	v_mfma_f32_16x16x32_bf16 v[56:59], v[126:129], v[114:117], v[56:59]
	v_mfma_f32_16x16x32_bf16 v[60:63], v[130:133], v[114:117], v[60:63]
	s_setprio 0
	s_waitcnt lgkmcnt(0)
	s_barrier
	s_cmpk_eq_i32 s0, 0x700
	s_cbranch_scc1 .Lnodma_g697
	s_add_u32 s100, s0, 0x80
	s_addc_u32 s101, s1, 0
	s_add_u32 s99, s98, s34
	s_setprio 1
	v_mfma_f32_16x16x32_bf16 v[36:39], v[150:153], v[134:137], v[36:39]
	v_mfma_f32_16x16x32_bf16 v[24:27], v[154:157], v[134:137], v[24:27]
	s_mov_b32 m0, s99
	v_lshl_add_u64 v[166:167], v[64:65], 0, s[100:101]
	global_load_lds_dwordx4 v[166:167], off
	v_mfma_f32_16x16x32_bf16 v[20:23], v[158:161], v[134:137], v[20:23]
	v_mfma_f32_16x16x32_bf16 v[16:19], v[162:165], v[134:137], v[16:19]
	s_add_u32 m0, s99, 0x4000
	v_lshl_add_u64 v[166:167], v[66:67], 0, s[100:101]
	global_load_lds_dwordx4 v[166:167], off
	v_mfma_f32_16x16x32_bf16 v[12:15], v[150:153], v[138:141], v[12:15]
	v_mfma_f32_16x16x32_bf16 v[8:11], v[154:157], v[138:141], v[8:11]
	s_add_u32 m0, s99, 0x1000
	v_lshl_add_u64 v[166:167], v[68:69], 0, s[100:101]
	global_load_lds_dwordx4 v[166:167], off
	v_mfma_f32_16x16x32_bf16 v[4:7], v[158:161], v[138:141], v[4:7]
	v_mfma_f32_16x16x32_bf16 v[0:3], v[162:165], v[138:141], v[0:3]
	s_add_u32 m0, s99, 0x5000
	v_lshl_add_u64 v[166:167], v[70:71], 0, s[100:101]
	global_load_lds_dwordx4 v[166:167], off
	v_mfma_f32_16x16x32_bf16 v[28:31], v[150:153], v[142:145], v[28:31]
	v_mfma_f32_16x16x32_bf16 v[32:35], v[154:157], v[142:145], v[32:35]
	s_add_u32 m0, s99, 0x2000
	v_lshl_add_u64 v[166:167], v[72:73], 0, s[100:101]
	global_load_lds_dwordx4 v[166:167], off
	v_mfma_f32_16x16x32_bf16 v[40:43], v[158:161], v[142:145], v[40:43]
	v_mfma_f32_16x16x32_bf16 v[44:47], v[162:165], v[142:145], v[44:47]
	s_add_u32 m0, s99, 0x6000
	v_lshl_add_u64 v[166:167], v[74:75], 0, s[100:101]
	global_load_lds_dwordx4 v[166:167], off
	v_mfma_f32_16x16x32_bf16 v[48:51], v[150:153], v[146:149], v[48:51]
	v_mfma_f32_16x16x32_bf16 v[52:55], v[154:157], v[146:149], v[52:55]
	s_add_u32 m0, s99, 0x3000
	v_lshl_add_u64 v[166:167], v[76:77], 0, s[100:101]
	global_load_lds_dwordx4 v[166:167], off
	v_mfma_f32_16x16x32_bf16 v[56:59], v[158:161], v[146:149], v[56:59]
	v_mfma_f32_16x16x32_bf16 v[60:63], v[162:165], v[146:149], v[60:63]
	s_add_u32 m0, s99, 0x7000
	v_lshl_add_u64 v[166:167], v[78:79], 0, s[100:101]
	global_load_lds_dwordx4 v[166:167], off
	s_setprio 0
	s_branch .Ljoin_g697
